# P0 wabT LDS fill: 8 loads per iteration issued together with counted vmcnt(7..0) instead of 4 serialized load pairs
# speedup vs baseline: 1.2471x; 1.0062x over previous
; DI void phase_prep(const Params& p, int bid, int nb, char* smem) {
;     ...
;   for (int i = tid; i < 8192; i += 256) { int k = i >> 3, j = i & 7; wabT[j * 1024 + k] = p.w_in[(size_t)k * INC + 3584 + j]; }
.LBB0_9:
	v_lshrrev_b32_e32 v154, 3, v4
	v_lshrrev_b32_e32 v155, 3, v5
	v_mad_u64_u32 v[150:151], s[4:5], v155, s3, v[2:3]
	v_mad_u64_u32 v[152:153], s[4:5], v154, s3, v[2:3]
	v_mov_b32_e32 v153, v7
	v_mov_b32_e32 v151, v7
	v_lshl_add_u64 v[152:153], v[152:153], 2, s[20:21]
	v_lshl_add_u64 v[150:151], v[150:151], 2, s[20:21]
	global_load_dword v152, v[152:153], off
	s_nop 0
	global_load_dword v150, v[150:151], off
	v_lshl_add_u32 v151, v154, 2, v3
	v_lshl_add_u32 v153, v155, 2, v3
	v_add_u32_e32 v6, -4, v6
	v_cmp_eq_u32_e32 vcc, 0, v6
	s_or_b64 s[0:1], vcc, s[0:1]
	v_add_u32_e32 v158, 0x200, v5
	v_add_u32_e32 v159, 0x200, v4
	v_lshrrev_b32_e32 v162, 3, v159
	v_lshrrev_b32_e32 v163, 3, v158
	v_mad_u64_u32 v[158:159], s[4:5], v163, s3, v[2:3]
	v_mad_u64_u32 v[160:161], s[4:5], v162, s3, v[2:3]
	v_mov_b32_e32 v161, v7
	v_mov_b32_e32 v159, v7
	v_lshl_add_u64 v[160:161], v[160:161], 2, s[20:21]
	v_lshl_add_u64 v[158:159], v[158:159], 2, s[20:21]
	global_load_dword v160, v[160:161], off
	s_nop 0
	global_load_dword v158, v[158:159], off
	v_lshl_add_u32 v159, v162, 2, v3
	v_lshl_add_u32 v161, v163, 2, v3
	v_add_u32_e32 v166, 0x400, v5
	v_add_u32_e32 v167, 0x400, v4
	v_lshrrev_b32_e32 v170, 3, v167
	v_lshrrev_b32_e32 v171, 3, v166
	v_mad_u64_u32 v[166:167], s[4:5], v171, s3, v[2:3]
	v_mad_u64_u32 v[168:169], s[4:5], v170, s3, v[2:3]
	v_mov_b32_e32 v169, v7
	v_mov_b32_e32 v167, v7
	v_lshl_add_u64 v[168:169], v[168:169], 2, s[20:21]
	v_lshl_add_u64 v[166:167], v[166:167], 2, s[20:21]
	global_load_dword v168, v[168:169], off
	s_nop 0
	global_load_dword v166, v[166:167], off
	v_lshl_add_u32 v167, v170, 2, v3
	v_lshl_add_u32 v169, v171, 2, v3
	v_add_u32_e32 v174, 0x600, v5
	v_add_u32_e32 v175, 0x600, v4
	v_lshrrev_b32_e32 v178, 3, v175
	v_lshrrev_b32_e32 v179, 3, v174
	v_mad_u64_u32 v[174:175], s[4:5], v179, s3, v[2:3]
	v_mad_u64_u32 v[176:177], s[4:5], v178, s3, v[2:3]
	v_mov_b32_e32 v177, v7
	v_mov_b32_e32 v175, v7
	v_lshl_add_u64 v[176:177], v[176:177], 2, s[20:21]
	v_lshl_add_u64 v[174:175], v[174:175], 2, s[20:21]
	global_load_dword v176, v[176:177], off
	s_nop 0
	global_load_dword v174, v[174:175], off
	v_lshl_add_u32 v175, v178, 2, v3
	v_add_u32_e32 v5, 0x800, v5
	v_add_u32_e32 v4, 0x800, v4
	v_lshl_add_u32 v177, v179, 2, v3
	s_waitcnt vmcnt(7)
	ds_write_b32 v151, v152 offset:256
	s_waitcnt vmcnt(6)
	ds_write_b32 v153, v150 offset:256
	s_waitcnt vmcnt(5)
	ds_write_b32 v159, v160 offset:256
	s_waitcnt vmcnt(4)
	ds_write_b32 v161, v158 offset:256
	s_waitcnt vmcnt(3)
	ds_write_b32 v167, v168 offset:256
	s_waitcnt vmcnt(2)
	ds_write_b32 v169, v166 offset:256
	s_waitcnt vmcnt(1)
	ds_write_b32 v175, v176 offset:256
	s_waitcnt vmcnt(0)
	ds_write_b32 v177, v174 offset:256
	s_andn2_b64 exec, exec, s[0:1]
	s_cbranch_execnz .LBB0_9
	s_or_b64 exec, exec, s[0:1]
	v_mov_b32_e32 v6, 0
	v_cmp_ne_u32_e64 s[4:5], 0, 0
	s_and_saveexec_b64 s[0:1], s[4:5]
	s_cbranch_execz .LBB0_13
	s_mov_b64 s[4:5], 0
	s_movk_i32 s3, 0xe08
	v_mov_b32_e32 v7, 0
